# final norm phase: nt hint on the f32 output stores (on v67)
# baseline (speedup 1.0000x reference)
; __device__ __forceinline__ float wave_sum_fast(float x) { x = reduce16(x); return (rl_(x, 0) + rl_(x, 16)) + (rl_(x, 32) + rl_(x, 48)); }
; __device__ __forceinline__ void final_norm_phase(const Ctx& F) {
;     ...
;     for (int ch = gw; ch < T / 4; ch += NGW) {
;         u32x4 raw[4][2]; float s[4];
; #pragma unroll
;         for (int u = 0; u < 4; ++u)
; #pragma unroll
;             for (int j = 0; j < 2; ++j) raw[u][j] = *(const u32x4*)(xf + (size_t)(4 * ch + u) * D + 8 * ln + 512 * j);
; #pragma unroll
;         for (int u = 0; u < 4; ++u) { s[u] = 0.f;
; #pragma unroll
;             for (int j = 0; j < 2; ++j) { float f[8]; unpack8(raw[u][j], f);
; #pragma unroll
;                 for (int e = 0; e < 8; ++e) s[u] += f[e] * f[e]; }
;             s[u] = wave_sum_fast(s[u]); }
; #pragma unroll
;         for (int u = 0; u < 4; ++u) { const float rstd = 1.0f / sqrtf(s[u] * (1.0f / D) + 1e-6f); float* xr = F.out + (size_t)(4 * ch + u) * D;
.LBB0_1763:
	s_ashr_i32 s3, s2, 31
	s_lshl_b64 s[0:1], s[2:3], 11
	s_add_i32 s8, s2, 1
	v_lshl_add_u64 v[16:17], v[40:41], 0, s[0:1]
	s_ashr_i32 s9, s8, 31
	global_load_dwordx4 v[44:47], v[16:17], off offset:1024
	global_load_dwordx4 v[48:51], v[16:17], off
	s_lshl_b64 s[0:1], s[8:9], 11
	s_add_i32 s6, s2, 2
	v_lshl_add_u64 v[52:53], v[40:41], 0, s[0:1]
	s_ashr_i32 s7, s6, 31
	s_add_i32 s4, s2, 3
	global_load_dwordx4 v[32:35], v[52:53], off offset:1024
	s_lshl_b64 s[0:1], s[6:7], 11
	s_ashr_i32 s5, s4, 31
	v_lshl_add_u64 v[54:55], v[40:41], 0, s[0:1]
	s_lshl_b64 s[0:1], s[4:5], 11
	v_lshl_add_u64 v[56:57], v[40:41], 0, s[0:1]
	global_load_dwordx4 v[24:27], v[54:55], off offset:1024
	global_load_dwordx4 v[16:19], v[56:57], off offset:1024
	global_load_dwordx4 v[36:39], v[52:53], off
	global_load_dwordx4 v[28:31], v[54:55], off
	global_load_dwordx4 v[20:23], v[56:57], off
	s_lshl_b64 s[0:1], s[2:3], 12
	v_lshl_add_u64 v[72:73], v[42:43], 0, s[0:1]
	s_add_i32 s10, s10, s11
	s_add_i32 s2, s2, s12
	s_waitcnt vmcnt(0)
	v_lshlrev_b32_e32 v84, 16, v44
	v_lshlrev_b32_e32 v68, 16, v48
	v_and_b32_e32 v69, 0xffff0000, v48
	v_lshlrev_b32_e32 v70, 16, v49
	v_and_b32_e32 v71, 0xffff0000, v49
	v_pk_mul_f32 v[86:87], v[68:69], v[68:69]
	v_pk_mul_f32 v[88:89], v[70:71], v[70:71]
	v_and_b32_e32 v62, 0xffff0000, v34
	v_lshlrev_b32_e32 v63, 16, v34
	v_and_b32_e32 v56, 0xffff0000, v35
	v_lshlrev_b32_e32 v57, 16, v35
	v_and_b32_e32 v34, 0xffff0000, v17
	v_lshlrev_b32_e32 v35, 16, v17
	v_add_f32_e32 v17, v86, v87
	v_lshlrev_b32_e32 v80, 16, v50
	v_and_b32_e32 v81, 0xffff0000, v50
	v_add_f32_e32 v17, v88, v17
	v_pk_mul_f32 v[90:91], v[80:81], v[80:81]
	v_add_f32_e32 v17, v89, v17
	v_lshlrev_b32_e32 v82, 16, v51
	v_and_b32_e32 v83, 0xffff0000, v51
	v_add_f32_e32 v17, v90, v17
	v_pk_mul_f32 v[92:93], v[82:83], v[82:83]
	v_add_f32_e32 v17, v91, v17
	v_and_b32_e32 v85, 0xffff0000, v44
	v_add_f32_e32 v17, v92, v17
	v_pk_mul_f32 v[94:95], v[84:85], v[84:85]
	v_add_f32_e32 v17, v93, v17
	v_and_b32_e32 v74, 0xffff0000, v45
	v_lshlrev_b32_e32 v75, 16, v45
	v_add_f32_e32 v17, v94, v17
	v_pk_mul_f32 v[50:51], v[74:75], v[74:75]
	v_add_f32_e32 v17, v95, v17
	v_and_b32_e32 v76, 0xffff0000, v46
	v_lshlrev_b32_e32 v77, 16, v46
	v_add_f32_e32 v17, v51, v17
	v_pk_mul_f32 v[52:53], v[76:77], v[76:77]
	v_add_f32_e32 v17, v50, v17
	v_and_b32_e32 v78, 0xffff0000, v47
	v_lshlrev_b32_e32 v79, 16, v47
	v_add_f32_e32 v17, v53, v17
	v_pk_mul_f32 v[54:55], v[78:79], v[78:79]
	v_add_f32_e32 v17, v52, v17
	v_add_f32_e32 v17, v55, v17
	v_add_f32_e32 v17, v54, v17
	v_and_b32_e32 v48, 0xffff0000, v25
	v_lshlrev_b32_e32 v49, 16, v25
	v_add_f32_dpp v17, v17, v17 quad_perm:[1,0,3,2] row_mask:0xf bank_mask:0xf bound_ctrl:1
	v_and_b32_e32 v64, 0xffff0000, v33
	v_lshlrev_b32_e32 v65, 16, v33
	v_add_f32_dpp v17, v17, v17 quad_perm:[2,3,0,1] row_mask:0xf bank_mask:0xf bound_ctrl:1
	v_and_b32_e32 v91, 0xffff0000, v32
	v_pk_mul_f32 v[96:97], v[64:65], v[64:65]
	v_add_f32_dpp v17, v17, v17 row_half_mirror row_mask:0xf bank_mask:0xf bound_ctrl:1
	v_pk_mul_f32 v[98:99], v[62:63], v[62:63]
	v_pk_mul_f32 v[100:101], v[56:57], v[56:57]
	v_add_f32_dpp v17, v17, v17 row_mirror row_mask:0xf bank_mask:0xf bound_ctrl:1
	v_pk_mul_f32 v[60:61], v[48:49], v[48:49]
	v_readlane_b32 s3, v17, 16
	v_readlane_b32 s14, v17, 48
	v_readlane_b32 s0, v17, 0
	v_readlane_b32 s1, v17, 32
	v_mov_b32_e32 v50, s3
	v_mov_b32_e32 v51, s14
	v_pk_add_f32 v[50:51], s[0:1], v[50:51]
	v_and_b32_e32 v46, 0xffff0000, v26
	v_add_f32_e32 v17, v50, v51
	v_fmamk_f32 v17, v17, 0x3a800000, v66
	v_mul_f32_e32 v25, 0x4f800000, v17
	v_cmp_gt_f32_e32 vcc, s13, v17
	v_lshlrev_b32_e32 v47, 16, v26
	v_pk_mul_f32 v[58:59], v[46:47], v[46:47]
	v_cndmask_b32_e32 v17, v17, v25, vcc
	v_sqrt_f32_e32 v25, v17
	v_and_b32_e32 v44, 0xffff0000, v27
	v_lshlrev_b32_e32 v45, 16, v27
	v_pk_mul_f32 v[86:87], v[44:45], v[44:45]
	v_add_u32_e32 v33, -1, v25
	v_add_u32_e32 v54, 1, v25
	v_fma_f32 v55, -v33, v25, v17
	v_fma_f32 v88, -v54, v25, v17
	v_cmp_ge_f32_e64 s[0:1], 0, v55
	v_pk_mul_f32 v[52:53], v[34:35], v[34:35]
	v_and_b32_e32 v26, 0xffff0000, v18
	v_cndmask_b32_e64 v25, v25, v33, s[0:1]
	v_cmp_lt_f32_e64 s[0:1], 0, v88
	v_lshlrev_b32_e32 v27, 16, v18
	v_pk_mul_f32 v[50:51], v[26:27], v[26:27]
	v_cndmask_b32_e64 v25, v25, v54, s[0:1]
	v_mul_f32_e32 v33, 0x37800000, v25
	v_cndmask_b32_e32 v25, v25, v33, vcc
	v_cmp_class_f32_e32 vcc, v17, v67
	v_and_b32_e32 v18, 0xffff0000, v19
	v_lshlrev_b32_e32 v19, 16, v19
	v_cndmask_b32_e32 v17, v25, v17, vcc
	v_div_scale_f32 v25, s[0:1], v17, v17, 1.0
	v_rcp_f32_e32 v33, v25
	v_div_scale_f32 v88, vcc, 1.0, v17, 1.0
	v_pk_mul_f32 v[54:55], v[18:19], v[18:19]
	v_fma_f32 v89, -v25, v33, 1.0
	v_fmac_f32_e32 v33, v89, v33
	v_mul_f32_e32 v89, v88, v33
	v_fma_f32 v90, -v25, v89, v88
	v_fmac_f32_e32 v89, v90, v33
	v_fma_f32 v25, -v25, v89, v88
	v_div_fmas_f32 v25, v25, v33, v89
	v_div_fixup_f32 v88, v25, v17, 1.0
	v_pk_mul_f32 v[68:69], v[88:89], v[68:69] op_sel_hi:[0,1]
	v_pk_mul_f32 v[70:71], v[88:89], v[70:71] op_sel_hi:[0,1]
	s_waitcnt lgkmcnt(0)
; __device__ __forceinline__ void final_norm_phase(const Ctx& F) {
;     ...
;         for (int u = 0; u < 4; ++u) { const float rstd = 1.0f / sqrtf(s[u] * (1.0f / D) + 1e-6f); float* xr = F.out + (size_t)(4 * ch + u) * D;
; #pragma unroll
;             for (int j = 0; j < 2; ++j) { float f[8]; unpack8(raw[u][j], f);
;                 *(f32x4*)(xr + 8 * ln + 512 * j) = (f32x4){f[0] * rstd * ga[j][0], f[1] * rstd * ga[j][1], f[2] * rstd * ga[j][2], f[3] * rstd * ga[j][3]};
;                 *(f32x4*)(xr + 8 * ln + 512 * j + 4) = (f32x4){f[4] * rstd * ga[j][4], f[5] * rstd * ga[j][5], f[6] * rstd * ga[j][6], f[7] * rstd * ga[j][7]}; } }
	v_pk_mul_f32 v[70:71], v[2:3], v[70:71]
	v_pk_mul_f32 v[68:69], v[0:1], v[68:69]
	global_store_dwordx4 v[72:73], v[68:71], off nt
	v_lshlrev_b32_e32 v90, 16, v32
	v_pk_mul_f32 v[32:33], v[90:91], v[90:91]
	v_pk_mul_f32 v[68:69], v[88:89], v[80:81] op_sel_hi:[0,1]
	v_pk_mul_f32 v[70:71], v[88:89], v[82:83] op_sel_hi:[0,1]
	v_pk_mul_f32 v[70:71], v[6:7], v[70:71]
	v_pk_mul_f32 v[68:69], v[4:5], v[68:69]
	global_store_dwordx4 v[72:73], v[68:71], off offset:16 nt
	v_lshlrev_b32_e32 v80, 16, v38
	v_and_b32_e32 v81, 0xffff0000, v38
	v_pk_mul_f32 v[68:69], v[88:89], v[84:85] op_sel_hi:[0,1]
	v_pk_mul_f32 v[70:71], v[88:89], v[74:75] op_sel_hi:[0,1]
	v_pk_mul_f32 v[70:71], v[10:11], v[70:71] op_sel:[0,1] op_sel_hi:[1,0]
	v_pk_mul_f32 v[68:69], v[8:9], v[68:69]
	global_store_dwordx4 v[72:73], v[68:71], off offset:2048 nt
	v_pk_mul_f32 v[82:83], v[80:81], v[80:81]
	v_lshlrev_b32_e32 v84, 16, v39
	v_lshlrev_b32_e32 v70, 16, v36
	v_and_b32_e32 v71, 0xffff0000, v36
	v_pk_mul_f32 v[68:69], v[88:89], v[76:77] op_sel_hi:[0,1]
	v_pk_mul_f32 v[74:75], v[70:71], v[70:71]
	v_lshlrev_b32_e32 v76, 16, v37
	v_and_b32_e32 v77, 0xffff0000, v37
	v_pk_mul_f32 v[36:37], v[76:77], v[76:77]
	v_add_f32_e32 v17, v74, v75
	v_add_f32_e32 v17, v36, v17
	v_add_f32_e32 v17, v37, v17
	v_and_b32_e32 v85, 0xffff0000, v39
	v_add_f32_e32 v17, v82, v17
	v_pk_mul_f32 v[38:39], v[84:85], v[84:85]
	v_add_f32_e32 v17, v83, v17
	v_add_f32_e32 v17, v38, v17
	v_add_f32_e32 v17, v39, v17
	v_add_f32_e32 v17, v32, v17
	v_add_f32_e32 v17, v33, v17
	v_add_f32_e32 v17, v97, v17
	v_add_f32_e32 v17, v96, v17
	v_add_f32_e32 v17, v99, v17
	v_add_f32_e32 v17, v98, v17
	v_add_f32_e32 v17, v101, v17
	v_add_f32_e32 v17, v100, v17
	v_pk_mul_f32 v[36:37], v[12:13], v[68:69] op_sel:[0,1] op_sel_hi:[1,0]
	v_lshlrev_b32_e32 v74, 16, v31
	v_add_f32_dpp v17, v17, v17 quad_perm:[1,0,3,2] row_mask:0xf bank_mask:0xf bound_ctrl:1
	v_and_b32_e32 v75, 0xffff0000, v31
	s_nop 0
	v_add_f32_dpp v17, v17, v17 quad_perm:[2,3,0,1] row_mask:0xf bank_mask:0xf bound_ctrl:1
	s_nop 1
	v_add_f32_dpp v17, v17, v17 row_half_mirror row_mask:0xf bank_mask:0xf bound_ctrl:1
	s_nop 1
	v_add_f32_dpp v17, v17, v17 row_mirror row_mask:0xf bank_mask:0xf bound_ctrl:1
	s_nop 0
	v_readlane_b32 s3, v17, 16
	v_readlane_b32 s14, v17, 48
	v_readlane_b32 s0, v17, 0
	v_readlane_b32 s1, v17, 32
	v_mov_b32_e32 v32, s3
	v_mov_b32_e32 v33, s14
	v_pk_add_f32 v[32:33], s[0:1], v[32:33]
	s_nop 0
	v_add_f32_e32 v17, v32, v33
	v_fmamk_f32 v17, v17, 0x3a800000, v66
	v_mul_f32_e32 v25, 0x4f800000, v17
	v_cmp_gt_f32_e32 vcc, s13, v17
	v_pk_mul_f32 v[32:33], v[88:89], v[78:79] op_sel_hi:[0,1]
	v_pk_mul_f32 v[38:39], v[14:15], v[32:33] op_sel:[0,1] op_sel_hi:[1,0]
	v_cndmask_b32_e32 v17, v17, v25, vcc
	v_sqrt_f32_e32 v25, v17
	global_store_dwordx4 v[72:73], v[36:39], off offset:2064 nt
	v_add_u32_e32 v32, -1, v25
	v_fma_f32 v33, -v32, v25, v17
	v_cmp_ge_f32_e64 s[0:1], 0, v33
	v_add_u32_e32 v33, 1, v25
	s_nop 0
	v_cndmask_b32_e64 v32, v25, v32, s[0:1]
	v_fma_f32 v25, -v33, v25, v17
	v_cmp_lt_f32_e64 s[0:1], 0, v25
	s_nop 1
	v_cndmask_b32_e64 v25, v32, v33, s[0:1]
	v_mul_f32_e32 v32, 0x37800000, v25
	v_cndmask_b32_e32 v25, v25, v32, vcc
	v_cmp_class_f32_e32 vcc, v17, v67
	s_nop 1
	v_cndmask_b32_e32 v17, v25, v17, vcc
	v_div_scale_f32 v25, s[0:1], v17, v17, 1.0
	v_rcp_f32_e32 v68, v25
	s_lshl_b64 s[0:1], s[8:9], 12
	v_lshl_add_u64 v[32:33], v[42:43], 0, s[0:1]
	v_fma_f32 v36, -v25, v68, 1.0
	v_fmac_f32_e32 v68, v36, v68
	v_div_scale_f32 v36, vcc, 1.0, v17, 1.0
	v_mul_f32_e32 v37, v36, v68
	v_fma_f32 v38, -v25, v37, v36
	v_fmac_f32_e32 v37, v38, v68
	v_fma_f32 v25, -v25, v37, v36
	v_div_fmas_f32 v25, v25, v68, v37
	v_div_fixup_f32 v68, v25, v17, 1.0
	v_pk_mul_f32 v[36:37], v[68:69], v[70:71] op_sel_hi:[0,1]
	v_pk_mul_f32 v[38:39], v[68:69], v[76:77] op_sel_hi:[0,1]
	v_pk_mul_f32 v[38:39], v[2:3], v[38:39]
	v_pk_mul_f32 v[36:37], v[0:1], v[36:37]
	global_store_dwordx4 v[32:33], v[36:39], off nt
	v_lshlrev_b32_e32 v70, 16, v30
	v_and_b32_e32 v71, 0xffff0000, v30
	v_pk_mul_f32 v[36:37], v[68:69], v[80:81] op_sel_hi:[0,1]
	v_pk_mul_f32 v[38:39], v[68:69], v[84:85] op_sel_hi:[0,1]
	v_pk_mul_f32 v[38:39], v[6:7], v[38:39]
	v_pk_mul_f32 v[36:37], v[4:5], v[36:37]
	global_store_dwordx4 v[32:33], v[36:39], off offset:16 nt
	v_pk_mul_f32 v[72:73], v[70:71], v[70:71]
	v_pk_mul_f32 v[30:31], v[74:75], v[74:75]
	v_pk_mul_f32 v[36:37], v[68:69], v[90:91] op_sel_hi:[0,1]
	v_pk_mul_f32 v[38:39], v[68:69], v[64:65] op_sel_hi:[0,1]
	v_pk_mul_f32 v[38:39], v[10:11], v[38:39] op_sel:[0,1] op_sel_hi:[1,0]
	v_pk_mul_f32 v[36:37], v[8:9], v[36:37]
	global_store_dwordx4 v[32:33], v[36:39], off offset:2048 nt
	v_lshlrev_b32_e32 v64, 16, v29
	v_and_b32_e32 v65, 0xffff0000, v29
	v_lshlrev_b32_e32 v38, 16, v28
	v_and_b32_e32 v39, 0xffff0000, v28
	v_pk_mul_f32 v[36:37], v[68:69], v[62:63] op_sel_hi:[0,1]
	v_pk_mul_f32 v[62:63], v[38:39], v[38:39]
	v_pk_mul_f32 v[28:29], v[64:65], v[64:65]
	v_add_f32_e32 v17, v62, v63
	v_add_f32_e32 v17, v28, v17
	v_add_f32_e32 v17, v29, v17
	v_add_f32_e32 v17, v72, v17
	v_add_f32_e32 v17, v73, v17
	v_lshlrev_b32_e32 v76, 16, v24
	v_and_b32_e32 v77, 0xffff0000, v24
	v_add_f32_e32 v17, v30, v17
	v_pk_mul_f32 v[24:25], v[76:77], v[76:77]
	v_add_f32_e32 v17, v31, v17
	v_add_f32_e32 v17, v24, v17
	v_add_f32_e32 v17, v25, v17
	v_add_f32_e32 v17, v61, v17
	v_add_f32_e32 v17, v60, v17
	v_add_f32_e32 v17, v59, v17
	v_add_f32_e32 v17, v58, v17
	v_add_f32_e32 v17, v87, v17
	v_add_f32_e32 v17, v86, v17
	v_pk_mul_f32 v[28:29], v[12:13], v[36:37] op_sel:[0,1] op_sel_hi:[1,0]
	v_and_b32_e32 v59, 0xffff0000, v16
	v_add_f32_dpp v17, v17, v17 quad_perm:[1,0,3,2] row_mask:0xf bank_mask:0xf bound_ctrl:1
; __device__ __forceinline__ float wave_sum_fast(float x) { x = reduce16(x); return (rl_(x, 0) + rl_(x, 16)) + (rl_(x, 32) + rl_(x, 48)); }
; __device__ __forceinline__ void final_norm_phase(const Ctx& F) {
;     ...
;         for (int u = 0; u < 4; ++u) { s[u] = 0.f;
; #pragma unroll
;             for (int j = 0; j < 2; ++j) { float f[8]; unpack8(raw[u][j], f);
; #pragma unroll
;                 for (int e = 0; e < 8; ++e) s[u] += f[e] * f[e]; }
;             s[u] = wave_sum_fast(s[u]); }
; #pragma unroll
;         for (int u = 0; u < 4; ++u) { const float rstd = 1.0f / sqrtf(s[u] * (1.0f / D) + 1e-6f); float* xr = F.out + (size_t)(4 * ch + u) * D;
; #pragma unroll
;             for (int j = 0; j < 2; ++j) { float f[8]; unpack8(raw[u][j], f);
;                 *(f32x4*)(xr + 8 * ln + 512 * j) = (f32x4){f[0] * rstd * ga[j][0], f[1] * rstd * ga[j][1], f[2] * rstd * ga[j][2], f[3] * rstd * ga[j][3]};
;                 *(f32x4*)(xr + 8 * ln + 512 * j + 4) = (f32x4){f[4] * rstd * ga[j][4], f[5] * rstd * ga[j][5], f[6] * rstd * ga[j][6], f[7] * rstd * ga[j][7]}; } }
;     }
	s_nop 1
	v_add_f32_dpp v17, v17, v17 quad_perm:[2,3,0,1] row_mask:0xf bank_mask:0xf bound_ctrl:1
	s_nop 1
	v_add_f32_dpp v17, v17, v17 row_half_mirror row_mask:0xf bank_mask:0xf bound_ctrl:1
	s_nop 1
	v_add_f32_dpp v17, v17, v17 row_mirror row_mask:0xf bank_mask:0xf bound_ctrl:1
	s_nop 0
	v_readlane_b32 s3, v17, 16
	v_readlane_b32 s8, v17, 48
	v_readlane_b32 s0, v17, 0
	v_readlane_b32 s1, v17, 32
	v_mov_b32_e32 v24, s3
	v_mov_b32_e32 v25, s8
	v_pk_add_f32 v[24:25], s[0:1], v[24:25]
	s_nop 0
	v_add_f32_e32 v17, v24, v25
	v_fmamk_f32 v17, v17, 0x3a800000, v66
	v_mul_f32_e32 v24, 0x4f800000, v17
	v_cmp_gt_f32_e32 vcc, s13, v17
	s_nop 1
	v_cndmask_b32_e32 v17, v17, v24, vcc
	v_sqrt_f32_e32 v58, v17
	v_pk_mul_f32 v[24:25], v[68:69], v[56:57] op_sel_hi:[0,1]
	v_pk_mul_f32 v[30:31], v[14:15], v[24:25] op_sel:[0,1] op_sel_hi:[1,0]
	global_store_dwordx4 v[32:33], v[28:31], off offset:2064 nt
	v_add_u32_e32 v24, -1, v58
	v_fma_f32 v25, -v24, v58, v17
	v_cmp_ge_f32_e64 s[0:1], 0, v25
	v_add_u32_e32 v25, 1, v58
	v_fma_f32 v36, -v25, v58, v17
	v_cndmask_b32_e64 v24, v58, v24, s[0:1]
	v_cmp_lt_f32_e64 s[0:1], 0, v36
	v_lshlrev_b32_e32 v56, 16, v23
	v_and_b32_e32 v57, 0xffff0000, v23
	v_cndmask_b32_e64 v24, v24, v25, s[0:1]
	v_mul_f32_e32 v25, 0x37800000, v24
	v_cndmask_b32_e32 v24, v24, v25, vcc
	v_cmp_class_f32_e32 vcc, v17, v67
	v_lshlrev_b32_e32 v58, 16, v16
	s_nop 0
	v_cndmask_b32_e32 v17, v24, v17, vcc
	v_div_scale_f32 v36, s[0:1], v17, v17, 1.0
	v_rcp_f32_e32 v37, v36
	s_lshl_b64 s[0:1], s[6:7], 12
	v_lshl_add_u64 v[24:25], v[42:43], 0, s[0:1]
	v_fma_f32 v28, -v36, v37, 1.0
	v_fmac_f32_e32 v37, v28, v37
	v_div_scale_f32 v28, vcc, 1.0, v17, 1.0
	v_mul_f32_e32 v29, v28, v37
	v_fma_f32 v30, -v36, v29, v28
	v_fmac_f32_e32 v29, v30, v37
	v_fma_f32 v28, -v36, v29, v28
	v_div_fmas_f32 v28, v28, v37, v29
	v_div_fixup_f32 v32, v28, v17, 1.0
	v_pk_mul_f32 v[28:29], v[32:33], v[38:39] op_sel_hi:[0,1]
	v_pk_mul_f32 v[30:31], v[32:33], v[64:65] op_sel_hi:[0,1]
	v_pk_mul_f32 v[30:31], v[2:3], v[30:31]
	v_pk_mul_f32 v[28:29], v[0:1], v[28:29]
	global_store_dwordx4 v[24:25], v[28:31], off nt
	v_lshlrev_b32_e32 v38, 16, v21
	v_and_b32_e32 v39, 0xffff0000, v21
	v_pk_mul_f32 v[28:29], v[32:33], v[70:71] op_sel_hi:[0,1]
	v_pk_mul_f32 v[30:31], v[32:33], v[74:75] op_sel_hi:[0,1]
	v_pk_mul_f32 v[30:31], v[6:7], v[30:31]
	v_pk_mul_f32 v[28:29], v[4:5], v[28:29]
	global_store_dwordx4 v[24:25], v[28:31], off offset:16 nt
	v_pk_mul_f32 v[16:17], v[58:59], v[58:59]
	s_nop 0
	v_pk_mul_f32 v[28:29], v[32:33], v[76:77] op_sel_hi:[0,1]
	v_pk_mul_f32 v[30:31], v[32:33], v[48:49] op_sel_hi:[0,1]
	v_pk_mul_f32 v[30:31], v[10:11], v[30:31] op_sel:[0,1] op_sel_hi:[1,0]
	v_pk_mul_f32 v[28:29], v[8:9], v[28:29]
	global_store_dwordx4 v[24:25], v[28:31], off offset:2048 nt
	s_nop 1
	v_lshlrev_b32_e32 v30, 16, v20
	v_and_b32_e32 v31, 0xffff0000, v20
	v_pk_mul_f32 v[36:37], v[30:31], v[30:31]
	v_pk_mul_f32 v[28:29], v[32:33], v[46:47] op_sel_hi:[0,1]
	v_pk_mul_f32 v[20:21], v[38:39], v[38:39]
	v_add_f32_e32 v33, v36, v37
	v_lshlrev_b32_e32 v46, 16, v22
	v_and_b32_e32 v47, 0xffff0000, v22
	v_add_f32_e32 v20, v20, v33
	v_pk_mul_f32 v[48:49], v[46:47], v[46:47]
	v_add_f32_e32 v20, v21, v20
	v_add_f32_e32 v20, v48, v20
	v_pk_mul_f32 v[22:23], v[56:57], v[56:57]
	v_add_f32_e32 v20, v49, v20
	v_add_f32_e32 v20, v22, v20
	v_add_f32_e32 v20, v23, v20
	v_add_f32_e32 v16, v16, v20
	v_add_f32_e32 v16, v17, v16
	v_add_f32_e32 v16, v53, v16
	v_add_f32_e32 v16, v52, v16
	v_add_f32_e32 v16, v51, v16
	v_add_f32_e32 v16, v50, v16
	v_add_f32_e32 v16, v55, v16
	v_add_f32_e32 v16, v54, v16
	v_pk_mul_f32 v[20:21], v[12:13], v[28:29] op_sel:[0,1] op_sel_hi:[1,0]
	s_nop 0
	v_add_f32_dpp v16, v16, v16 quad_perm:[1,0,3,2] row_mask:0xf bank_mask:0xf bound_ctrl:1
	s_nop 1
	v_add_f32_dpp v16, v16, v16 quad_perm:[2,3,0,1] row_mask:0xf bank_mask:0xf bound_ctrl:1
	s_nop 1
	v_add_f32_dpp v16, v16, v16 row_half_mirror row_mask:0xf bank_mask:0xf bound_ctrl:1
	s_nop 1
	v_add_f32_dpp v16, v16, v16 row_mirror row_mask:0xf bank_mask:0xf bound_ctrl:1
	s_nop 0
	v_readlane_b32 s3, v16, 16
	v_readlane_b32 s6, v16, 48
	v_readlane_b32 s0, v16, 0
	v_readlane_b32 s1, v16, 32
	v_mov_b32_e32 v16, s3
	v_mov_b32_e32 v17, s6
	v_pk_add_f32 v[16:17], s[0:1], v[16:17]
	s_nop 0
	v_add_f32_e32 v16, v16, v17
	v_fmamk_f32 v16, v16, 0x3a800000, v66
	v_mul_f32_e32 v17, 0x4f800000, v16
	v_cmp_gt_f32_e32 vcc, s13, v16
	s_nop 1
	v_cndmask_b32_e32 v33, v16, v17, vcc
	v_sqrt_f32_e32 v36, v33
	v_pk_mul_f32 v[16:17], v[32:33], v[44:45] op_sel_hi:[0,1]
	v_pk_mul_f32 v[22:23], v[14:15], v[16:17] op_sel:[0,1] op_sel_hi:[1,0]
	global_store_dwordx4 v[24:25], v[20:23], off offset:2064 nt
	v_add_u32_e32 v16, -1, v36
	v_fma_f32 v17, -v16, v36, v33
	v_cmp_ge_f32_e64 s[0:1], 0, v17
	v_add_u32_e32 v17, 1, v36
	v_fma_f32 v28, -v17, v36, v33
	v_cndmask_b32_e64 v16, v36, v16, s[0:1]
	v_cmp_lt_f32_e64 s[0:1], 0, v28
	s_nop 1
	v_cndmask_b32_e64 v16, v16, v17, s[0:1]
	v_mul_f32_e32 v17, 0x37800000, v16
	v_cndmask_b32_e32 v16, v16, v17, vcc
	v_cmp_class_f32_e32 vcc, v33, v67
	s_nop 1
	v_cndmask_b32_e32 v16, v16, v33, vcc
	v_div_scale_f32 v17, s[0:1], v16, v16, 1.0
	v_rcp_f32_e32 v28, v17
	s_lshl_b64 s[0:1], s[4:5], 12
	v_lshl_add_u64 v[24:25], v[42:43], 0, s[0:1]
	s_cmpk_lt_i32 s10, 0x4000
	v_fma_f32 v20, -v17, v28, 1.0
	v_fmac_f32_e32 v28, v20, v28
	v_div_scale_f32 v20, vcc, 1.0, v16, 1.0
	v_mul_f32_e32 v21, v20, v28
	v_fma_f32 v22, -v17, v21, v20
	v_fmac_f32_e32 v21, v22, v28
	v_fma_f32 v17, -v17, v21, v20
	v_div_fmas_f32 v17, v17, v28, v21
	v_div_fixup_f32 v16, v17, v16, 1.0
	v_pk_mul_f32 v[20:21], v[16:17], v[30:31] op_sel_hi:[0,1]
	v_pk_mul_f32 v[22:23], v[16:17], v[38:39] op_sel_hi:[0,1]
	v_pk_mul_f32 v[22:23], v[2:3], v[22:23]
	v_pk_mul_f32 v[20:21], v[0:1], v[20:21]
	global_store_dwordx4 v[24:25], v[20:23], off nt
	s_nop 1
	v_pk_mul_f32 v[20:21], v[16:17], v[46:47] op_sel_hi:[0,1]
	v_pk_mul_f32 v[22:23], v[16:17], v[56:57] op_sel_hi:[0,1]
	v_pk_mul_f32 v[22:23], v[6:7], v[22:23]
	v_pk_mul_f32 v[20:21], v[4:5], v[20:21]
	global_store_dwordx4 v[24:25], v[20:23], off offset:16 nt
	s_nop 1
	v_pk_mul_f32 v[20:21], v[16:17], v[58:59] op_sel_hi:[0,1]
	v_pk_mul_f32 v[22:23], v[16:17], v[34:35] op_sel_hi:[0,1]
	v_pk_mul_f32 v[22:23], v[10:11], v[22:23] op_sel:[0,1] op_sel_hi:[1,0]
	v_pk_mul_f32 v[20:21], v[8:9], v[20:21]
	global_store_dwordx4 v[24:25], v[20:23], off offset:2048 nt
	s_nop 1
	v_pk_mul_f32 v[20:21], v[16:17], v[26:27] op_sel_hi:[0,1]
	v_pk_mul_f32 v[16:17], v[16:17], v[18:19] op_sel_hi:[0,1]
	v_pk_mul_f32 v[18:19], v[14:15], v[16:17] op_sel:[0,1] op_sel_hi:[1,0]
	v_pk_mul_f32 v[16:17], v[12:13], v[20:21] op_sel:[0,1] op_sel_hi:[1,0]
	global_store_dwordx4 v[24:25], v[16:19], off offset:2064 nt
	s_cbranch_scc1 .LBB0_1763
